# attention work queue: next-item atomic issued one item further ahead with no wait at item start; s_item words accessed by ds_read/ds_write so the loop head no longer waits vmcnt(0) on outstanding stor
# baseline (speedup 1.0000x reference)
; __global__ void __launch_bounds__(512, 2) mega(Params p) {
;     ...
;       if (tid == 0) s_item[0] = atomicAdd(&CTR[layer], 1);
.LBB0_1233:
	v_readlane_b32 s0, v254, 41
	v_readlane_b32 s1, v254, 42
	s_mov_b32 s1, s55
	v_writelane_b32 v254, s0, 41
	s_nop 1
	v_writelane_b32 v254, s1, 42
	s_mov_b64 s[0:1], exec
	v_readlane_b32 s8, v250, 2
	v_readlane_b32 s9, v250, 3
	s_and_b64 s[8:9], s[0:1], s[8:9]
	s_mov_b64 exec, s[8:9]
	s_cbranch_execz .LBB0_1237
	s_mov_b64 s[10:11], exec
	v_mbcnt_lo_u32_b32 v0, s10, 0
	v_mbcnt_hi_u32_b32 v0, s11, v0
	v_cmp_eq_u32_e32 vcc, 0, v0
	s_and_saveexec_b64 s[8:9], vcc
	s_cbranch_execz .LBB0_1236
	v_readlane_b32 s12, v254, 41
	v_readlane_b32 s13, v254, 42
	s_lshl_b64 s[12:13], s[12:13], 2
	v_readlane_b32 s14, v250, 48
	s_add_u32 s12, s14, s12
	v_readlane_b32 s14, v250, 49
	s_addc_u32 s13, s14, s13
	s_bcnt1_i32_b64 s10, s[10:11]
	v_mov_b32_e32 v2, s10
	global_atomic_add v2, v1, v2, s[12:13] sc0
	v_mov_b32_e32 v241, s10
	global_atomic_add v241, v1, v241, s[12:13] sc0

; __global__ void __launch_bounds__(512, 2) mega(Params p) {
;     ...
;       for (int par = 0;; par ^= 1) {
;         const int item = __builtin_amdgcn_readfirstlane(s_item[par]);
;         if (item >= total) break;
;         if (tid == 0) s_item[par ^ 1] = atomicAdd(&CTR[layer], 1);
.LBB0_1241:
	s_lshl_b32 s0, s25, 2
	s_add_i32 s0, s0, 0
	s_add_i32 s0, s0, 0x24a00
	v_mov_b32_e32 v2, s0
	v_readlane_b32 s0, v250, 42
	v_readlane_b32 s1, v250, 43
	s_nop 1
	v_mov_b32_e32 v3, s1
	ds_read_b32 v0, v2
	s_mov_b64 s[0:1], -1
	s_waitcnt lgkmcnt(0)
	v_readfirstlane_b32 s26, v0
	s_cmp_ge_i32 s26, s23
	s_cbranch_scc1 .LBB0_1240
	s_mov_b64 s[0:1], exec
	v_readlane_b32 s8, v250, 2
	v_readlane_b32 s9, v250, 3
	s_and_b64 s[8:9], s[0:1], s[8:9]
	s_mov_b64 exec, s[8:9]
	s_cbranch_execnz .LBB0_1245
	s_or_b64 exec, exec, s[0:1]
	s_cmp_ge_i32 s26, s22
	s_mov_b64 s[0:1], -1
	s_cbranch_scc1 .LBB0_1248

; __global__ void __launch_bounds__(512, 2) mega(Params p) {
;     ...
;         if (tid == 0) s_item[par ^ 1] = atomicAdd(&CTR[layer], 1);
.LBB0_1245:
	s_mov_b64 s[10:11], exec
	v_mbcnt_lo_u32_b32 v0, s10, 0
	v_mbcnt_hi_u32_b32 v0, s11, v0
	v_cmp_eq_u32_e32 vcc, 0, v0
	s_and_saveexec_b64 s[8:9], vcc
	s_cbranch_execz .LBB0_1247
	v_mov_b32_e32 v2, v241
	s_bcnt1_i32_b64 s10, s[10:11]
	v_mov_b32_e32 v241, s10
	global_atomic_add v241, v1, v241, s[78:79] sc0
.LBB0_1247:
	s_or_b64 exec, exec, s[8:9]
	s_xor_b32 s8, s25, 1
	s_lshl_b32 s8, s8, 2
	s_add_i32 s8, s8, 0
	s_add_i32 s8, s8, 0x24a00
	v_mov_b32_e32 v4, s8
	v_readfirstlane_b32 s8, v2
	s_nop 0
	v_add_u32_e32 v0, s8, v0
	ds_write_b32 v4, v0
	s_waitcnt lgkmcnt(0)
	s_or_b64 exec, exec, s[0:1]
	s_cmp_ge_i32 s26, s22
	s_mov_b64 s[0:1], -1
	s_cbranch_scc0 .LBB0_1244
